# hgrn_h1: the V-column loads of a thread issued with its gate loads at the top of the item (two exposed round trips per item removed)
# speedup vs baseline: 1.0082x; 1.0021x over previous
; __device__ __forceinline__ unsigned short bf1(float f) { return (unsigned short)(pk2(f, 0.f) & 0xffffu); }
; __device__ __forceinline__ void hgrn_h1(LAS unsigned char* lds8, const int e) {
;     ...
;         { const float* vs = PROJ + (size_t)(m0 + 16 * J) * IN_EVEN + 2048 + h * 128 + k;
; #pragma unroll
;           for (int jj = 0; jj < 16; ++jj) VT[k * RS64 + 16 * J + jj] = bf1(vs[(size_t)jj * IN_EVEN]); }
.LBB0_1019:
	s_and_b32 s3, s4, 0xfffff000
	s_and_b32 s10, s26, 0xfc0
	s_or_b32 s3, s3, s10
	v_add_u32_e32 v10, s3, v30
	v_mov_b64_e32 v[12:13], s[14:15]
	v_mad_i64_i32 v[12:13], s[10:11], v10, s33, v[12:13]
	v_lshl_add_u64 v[12:13], s[52:53], 2, v[12:13]
	v_lshl_add_u64 v[12:13], v[12:13], 0, v[2:3]
	s_movk_i32 s3, 0x2000
	v_add_co_u32_e32 v24, vcc, s3, v12
	s_nop 1
	v_addc_co_u32_e32 v25, vcc, 0, v13, vcc
	s_barrier
	global_load_dword v33, v[24:25], off offset:-4096
	s_movk_i32 s3, 0x6000
	v_add_co_u32_e32 v14, vcc, s3, v12
	s_mov_b32 s3, 0xd000
	s_nop 0
	v_addc_co_u32_e32 v15, vcc, 0, v13, vcc
	global_load_dword v37, v[14:15], off offset:2048
	v_add_co_u32_e32 v26, vcc, s3, v12
	s_mov_b32 s3, 0x11000
	s_nop 0
	v_addc_co_u32_e32 v27, vcc, 0, v13, vcc
	global_load_dword v38, v[26:27], off offset:-4096
	v_add_co_u32_e32 v14, vcc, s3, v12
	s_mov_b32 s3, 0x18000
	s_nop 0
	v_addc_co_u32_e32 v15, vcc, 0, v13, vcc
	v_add_co_u32_e32 v28, vcc, s3, v12
	s_mov_b32 s3, 0x1c000
	s_nop 0
	v_addc_co_u32_e32 v29, vcc, 0, v13, vcc
	global_load_dword v40, v[14:15], off offset:2048
	global_load_dword v42, v[28:29], off offset:-4096
	s_waitcnt vmcnt(5)
	v_sub_f32_e32 v10, 1.0, v57
	global_load_dword v24, v[24:25], off
	v_add_co_u32_e32 v14, vcc, s3, v12
	s_mov_b32 s3, 0x23000
	s_nop 0
	v_addc_co_u32_e32 v15, vcc, 0, v13, vcc
	v_add_co_u32_e32 v16, vcc, s3, v12
	s_mov_b32 s3, 0x27000
	s_nop 0
	v_addc_co_u32_e32 v17, vcc, 0, v13, vcc
	global_load_dword v43, v[14:15], off offset:2048
	v_add_co_u32_e32 v14, vcc, s3, v12
	s_mov_b32 s3, 0x2e000
	s_nop 0
	v_addc_co_u32_e32 v15, vcc, 0, v13, vcc
	v_add_co_u32_e32 v18, vcc, s3, v12
	s_mov_b32 s3, 0x32000
	s_nop 0
	v_addc_co_u32_e32 v19, vcc, 0, v13, vcc
	global_load_dword v46, v[14:15], off offset:2048
	global_load_dword v48, v[18:19], off offset:-4096
	v_add_co_u32_e32 v14, vcc, s3, v12
	s_mov_b32 s3, 0x39000
	s_nop 0
	v_addc_co_u32_e32 v15, vcc, 0, v13, vcc
	v_add_co_u32_e32 v20, vcc, s3, v12
	s_mov_b32 s3, 0x3d000
	s_nop 0
	v_addc_co_u32_e32 v21, vcc, 0, v13, vcc
	global_load_dword v50, v[14:15], off offset:2048
	global_load_dword v51, v[20:21], off offset:-4096
	v_add_co_u32_e32 v14, vcc, s3, v12
	s_mov_b32 s3, 0x44000
	s_nop 0
	v_addc_co_u32_e32 v15, vcc, 0, v13, vcc
	v_add_co_u32_e32 v22, vcc, s3, v12
	s_mov_b32 s3, 0x48000
	s_nop 0
	v_addc_co_u32_e32 v23, vcc, 0, v13, vcc
	global_load_dword v53, v[14:15], off offset:2048
	global_load_dword v54, v[22:23], off offset:-4096
	v_add_co_u32_e32 v14, vcc, s3, v12
	s_mov_b32 s3, 0x4f000
	s_nop 0
	v_addc_co_u32_e32 v15, vcc, 0, v13, vcc
	s_waitcnt vmcnt(12)
	v_mul_f32_e32 v33, 0xbfb8aa3b, v33
	v_exp_f32_e32 v33, v33
	global_load_dword v62, v[14:15], off offset:2048
	v_add_co_u32_e32 v14, vcc, s3, v12
	v_add_f32_e32 v33, 1.0, v33
	v_rcp_f32_e32 v36, v33
	v_addc_co_u32_e32 v15, vcc, 0, v13, vcc
	s_mov_b32 s3, 0x53000
	v_add_co_u32_e32 v34, vcc, s3, v12
	v_fma_f32 v33, v10, v36, v57
	s_nop 0
	v_addc_co_u32_e32 v35, vcc, 0, v13, vcc
	v_cmp_gt_f32_e32 vcc, s29, v33
	global_load_dword v44, v[16:17], off offset:-4096
	global_load_dword v64, v[34:35], off offset:2048
	global_load_dword v63, v[14:15], off offset:-4096
	s_mov_b64 s[72:73], 0x7800
	v_lshl_add_u64 v[176:177], v[12:13], 0, s[72:73]
	global_load_dword v161, v[176:177], off
	s_mov_b64 s[72:73], 0xd000
	v_lshl_add_u64 v[176:177], v[12:13], 0, s[72:73]
	global_load_dword v162, v[176:177], off
	s_mov_b64 s[72:73], 0x12800
	v_lshl_add_u64 v[176:177], v[12:13], 0, s[72:73]
	global_load_dword v163, v[176:177], off
	s_mov_b64 s[72:73], 0x18000
	v_lshl_add_u64 v[176:177], v[12:13], 0, s[72:73]
	global_load_dword v164, v[176:177], off
	s_mov_b64 s[72:73], 0x1d800
	v_lshl_add_u64 v[176:177], v[12:13], 0, s[72:73]
	global_load_dword v165, v[176:177], off
	s_mov_b64 s[72:73], 0x23000
	v_lshl_add_u64 v[176:177], v[12:13], 0, s[72:73]
	global_load_dword v166, v[176:177], off
	s_mov_b64 s[72:73], 0x28800
	v_lshl_add_u64 v[176:177], v[12:13], 0, s[72:73]
	global_load_dword v167, v[176:177], off
	s_mov_b64 s[72:73], 0x2e000
	v_lshl_add_u64 v[176:177], v[12:13], 0, s[72:73]
	global_load_dword v168, v[176:177], off
	s_mov_b64 s[72:73], 0x33800
	v_lshl_add_u64 v[176:177], v[12:13], 0, s[72:73]
	global_load_dword v169, v[176:177], off
	s_mov_b64 s[72:73], 0x39000
	v_lshl_add_u64 v[176:177], v[12:13], 0, s[72:73]
	global_load_dword v170, v[176:177], off
	s_mov_b64 s[72:73], 0x3e800
	v_lshl_add_u64 v[176:177], v[12:13], 0, s[72:73]
	global_load_dword v171, v[176:177], off
	s_mov_b64 s[72:73], 0x44000
	v_lshl_add_u64 v[176:177], v[12:13], 0, s[72:73]
	global_load_dword v172, v[176:177], off
	s_mov_b64 s[72:73], 0x49800
	v_lshl_add_u64 v[176:177], v[12:13], 0, s[72:73]
	global_load_dword v173, v[176:177], off
	s_mov_b64 s[72:73], 0x4f000
	v_lshl_add_u64 v[176:177], v[12:13], 0, s[72:73]
	global_load_dword v174, v[176:177], off
	s_mov_b64 s[72:73], 0x54800
	v_lshl_add_u64 v[176:177], v[12:13], 0, s[72:73]
	global_load_dword v175, v[176:177], off
	v_cndmask_b32_e64 v34, 0, 32, vcc
	v_ldexp_f32 v33, v33, v34
	v_log_f32_e32 v33, v33
	s_movk_i32 s3, 0x7000
	v_mul_f32_e32 v34, 0x3f317217, v33
	v_fma_f32 v34, v33, s69, -v34
	v_fmac_f32_e32 v34, 0x3377d1cf, v33
	v_fmac_f32_e32 v34, 0x3f317217, v33
	v_cmp_lt_f32_e64 s[10:11], |v33|, s60
	s_waitcnt vmcnt(16)
	v_mul_f32_e32 v64, 0xbfb8aa3b, v64
	v_cndmask_b32_e64 v33, v33, v34, s[10:11]
	v_cndmask_b32_e32 v34, 0, v153, vcc
	v_sub_f32_e32 v33, v33, v34
	v_mul_f32_e32 v34, 0xbfb8aa3b, v37
	v_exp_f32_e32 v34, v34
	v_add_f32_e32 v33, 0, v33
	v_exp_f32_e32 v64, v64
	v_add_f32_e32 v34, 1.0, v34
	v_rcp_f32_e32 v39, v34
	v_add_f32_e32 v64, 1.0, v64
	v_rcp_f32_e32 v64, v64
	v_fma_f32 v34, v10, v39, v57
	v_cmp_gt_f32_e32 vcc, s29, v34
	s_nop 1
	v_cndmask_b32_e64 v35, 0, 32, vcc
	v_ldexp_f32 v34, v34, v35
	v_log_f32_e32 v34, v34
	s_nop 0
	v_mul_f32_e32 v35, 0x3f317217, v34
	v_fma_f32 v35, v34, s69, -v35
	v_fmac_f32_e32 v35, 0x3377d1cf, v34
	v_fmac_f32_e32 v35, 0x3f317217, v34
	v_cmp_lt_f32_e64 s[10:11], |v34|, s60
	s_nop 1
	v_cndmask_b32_e64 v34, v34, v35, s[10:11]
	v_cndmask_b32_e32 v35, 0, v153, vcc
	v_sub_f32_e32 v34, v34, v35
	v_mul_f32_e32 v35, 0xbfb8aa3b, v38
	v_exp_f32_e32 v35, v35
	v_add_f32_e32 v34, v33, v34
	v_add_f32_e32 v35, 1.0, v35
	v_rcp_f32_e32 v41, v35
	s_nop 0
	v_fma_f32 v35, v10, v41, v57
	v_cmp_gt_f32_e32 vcc, s29, v35
	s_nop 1
	v_cndmask_b32_e64 v37, 0, 32, vcc
	v_ldexp_f32 v35, v35, v37
	v_log_f32_e32 v35, v35
	s_nop 0
	v_mul_f32_e32 v37, 0x3f317217, v35
	v_fma_f32 v37, v35, s69, -v37
	v_fmac_f32_e32 v37, 0x3377d1cf, v35
	v_fmac_f32_e32 v37, 0x3f317217, v35
	v_cmp_lt_f32_e64 s[10:11], |v35|, s60
	s_nop 1
	v_cndmask_b32_e64 v35, v35, v37, s[10:11]
	v_cndmask_b32_e32 v37, 0, v153, vcc
	v_sub_f32_e32 v35, v35, v37
	v_mul_f32_e32 v37, 0xbfb8aa3b, v40
	v_exp_f32_e32 v37, v37
	v_add_f32_e32 v35, v34, v35
	v_add_f32_e32 v37, 1.0, v37
	v_rcp_f32_e32 v45, v37
	s_nop 0
	v_fma_f32 v37, v10, v45, v57
	v_cmp_gt_f32_e32 vcc, s29, v37
	s_nop 1
	v_cndmask_b32_e64 v38, 0, 32, vcc
	v_ldexp_f32 v37, v37, v38
	v_log_f32_e32 v37, v37
	s_nop 0
	v_mul_f32_e32 v38, 0x3f317217, v37
	v_fma_f32 v38, v37, s69, -v38
	v_fmac_f32_e32 v38, 0x3377d1cf, v37
	v_fmac_f32_e32 v38, 0x3f317217, v37
	v_cmp_lt_f32_e64 s[10:11], |v37|, s60
	s_nop 1
	v_cndmask_b32_e64 v37, v37, v38, s[10:11]
	v_cndmask_b32_e32 v38, 0, v153, vcc
	v_sub_f32_e32 v37, v37, v38
	v_mul_f32_e32 v38, 0xbfb8aa3b, v42
	v_exp_f32_e32 v38, v38
	v_add_f32_e32 v37, v35, v37
	v_add_f32_e32 v38, 1.0, v38
	v_rcp_f32_e32 v47, v38
	s_nop 0
	v_fma_f32 v38, v10, v47, v57
	v_cmp_gt_f32_e32 vcc, s29, v38
	s_nop 1
	v_cndmask_b32_e64 v40, 0, 32, vcc
	v_ldexp_f32 v38, v38, v40
	v_log_f32_e32 v38, v38
	s_nop 0
	v_mul_f32_e32 v40, 0x3f317217, v38
	v_fma_f32 v40, v38, s69, -v40
	v_fmac_f32_e32 v40, 0x3377d1cf, v38
	v_fmac_f32_e32 v40, 0x3f317217, v38
	v_cmp_lt_f32_e64 s[10:11], |v38|, s60
	s_nop 1
	v_cndmask_b32_e64 v38, v38, v40, s[10:11]
	v_cndmask_b32_e32 v40, 0, v153, vcc
	v_sub_f32_e32 v38, v38, v40
	v_mul_f32_e32 v40, 0xbfb8aa3b, v43
	v_exp_f32_e32 v40, v40
	v_add_f32_e32 v38, v37, v38
	v_add_f32_e32 v40, 1.0, v40
	v_rcp_f32_e32 v49, v40
	s_nop 0
	v_fma_f32 v40, v10, v49, v57
	v_cmp_gt_f32_e32 vcc, s29, v40
	s_nop 1
	v_cndmask_b32_e64 v42, 0, 32, vcc
	v_ldexp_f32 v40, v40, v42
	v_log_f32_e32 v40, v40
	s_nop 0
	v_mul_f32_e32 v42, 0x3f317217, v40
	v_fma_f32 v42, v40, s69, -v42
	v_fmac_f32_e32 v42, 0x3377d1cf, v40
	v_fmac_f32_e32 v42, 0x3f317217, v40
	v_cmp_lt_f32_e64 s[10:11], |v40|, s60
	s_nop 1
	v_cndmask_b32_e64 v40, v40, v42, s[10:11]
	v_cndmask_b32_e32 v42, 0, v153, vcc
	v_sub_f32_e32 v40, v40, v42
	v_mul_f32_e32 v42, 0xbfb8aa3b, v44
	v_exp_f32_e32 v42, v42
	v_add_f32_e32 v40, v38, v40
	v_add_f32_e32 v42, 1.0, v42
	v_rcp_f32_e32 v52, v42
	s_nop 0
	v_fma_f32 v42, v10, v52, v57
	v_cmp_gt_f32_e32 vcc, s29, v42
	s_nop 1
	v_cndmask_b32_e64 v43, 0, 32, vcc
	v_ldexp_f32 v42, v42, v43
	v_log_f32_e32 v42, v42
	s_nop 0
	v_mul_f32_e32 v43, 0x3f317217, v42
	v_fma_f32 v43, v42, s69, -v43
	v_fmac_f32_e32 v43, 0x3377d1cf, v42
	v_fmac_f32_e32 v43, 0x3f317217, v42
	v_cmp_lt_f32_e64 s[10:11], |v42|, s60
	s_nop 1
	v_cndmask_b32_e64 v42, v42, v43, s[10:11]
	v_cndmask_b32_e32 v43, 0, v153, vcc
	v_sub_f32_e32 v42, v42, v43
	v_mul_f32_e32 v43, 0xbfb8aa3b, v46
	v_exp_f32_e32 v43, v43
	v_add_f32_e32 v42, v40, v42
	v_add_f32_e32 v43, 1.0, v43
	v_rcp_f32_e32 v55, v43
	s_nop 0
	v_fma_f32 v43, v10, v55, v57
	v_cmp_gt_f32_e32 vcc, s29, v43
	s_nop 1
	v_cndmask_b32_e64 v44, 0, 32, vcc
	v_ldexp_f32 v43, v43, v44
	v_log_f32_e32 v43, v43
	s_nop 0
	v_mul_f32_e32 v44, 0x3f317217, v43
	v_fma_f32 v44, v43, s69, -v44
	v_fmac_f32_e32 v44, 0x3377d1cf, v43
	v_fmac_f32_e32 v44, 0x3f317217, v43
	v_cmp_lt_f32_e64 s[10:11], |v43|, s60
	s_nop 1
	v_cndmask_b32_e64 v43, v43, v44, s[10:11]
	v_cndmask_b32_e32 v44, 0, v153, vcc
	v_sub_f32_e32 v43, v43, v44
	v_add_f32_e32 v44, v42, v43
	v_mul_f32_e32 v43, 0xbfb8aa3b, v48
	v_exp_f32_e32 v43, v43
	s_nop 0
	v_add_f32_e32 v43, 1.0, v43
	v_rcp_f32_e32 v56, v43
	s_nop 0
	v_fma_f32 v43, v10, v56, v57
	v_cmp_gt_f32_e32 vcc, s29, v43
	s_nop 1
	v_cndmask_b32_e64 v46, 0, 32, vcc
	v_ldexp_f32 v43, v43, v46
	v_log_f32_e32 v43, v43
	s_nop 0
	v_mul_f32_e32 v46, 0x3f317217, v43
	v_fma_f32 v46, v43, s69, -v46
	v_fmac_f32_e32 v46, 0x3377d1cf, v43
	v_fmac_f32_e32 v46, 0x3f317217, v43
	v_cmp_lt_f32_e64 s[10:11], |v43|, s60
	s_nop 1
	v_cndmask_b32_e64 v43, v43, v46, s[10:11]
	v_cndmask_b32_e32 v46, 0, v153, vcc
; __device__ __forceinline__ unsigned short bf1(float f) { return (unsigned short)(pk2(f, 0.f) & 0xffffu); }
; __device__ __forceinline__ void hgrn_h1(LAS unsigned char* lds8, const int e) {
;     ...
;         { const float* vs = PROJ + (size_t)(m0 + 16 * J) * IN_EVEN + 2048 + h * 128 + k;
; #pragma unroll
;           for (int jj = 0; jj < 16; ++jj) VT[k * RS64 + 16 * J + jj] = bf1(vs[(size_t)jj * IN_EVEN]); }
;         __syncthreads();
;         { const float t0 = tots[k], t1 = tots[128 + k], t2 = tots[256 + k], t3 = tots[384 + k];
	v_sub_f32_e32 v43, v43, v46
	v_mul_f32_e32 v46, 0xbfb8aa3b, v50
	v_exp_f32_e32 v46, v46
	v_add_f32_e32 v43, v44, v43
	v_add_f32_e32 v46, 1.0, v46
	v_rcp_f32_e32 v58, v46
	s_nop 0
	v_fma_f32 v46, v10, v58, v57
	v_cmp_gt_f32_e32 vcc, s29, v46
	s_nop 1
	v_cndmask_b32_e64 v48, 0, 32, vcc
	v_ldexp_f32 v46, v46, v48
	v_log_f32_e32 v46, v46
	s_nop 0
	v_mul_f32_e32 v48, 0x3f317217, v46
	v_fma_f32 v48, v46, s69, -v48
	v_fmac_f32_e32 v48, 0x3377d1cf, v46
	v_fmac_f32_e32 v48, 0x3f317217, v46
	v_cmp_lt_f32_e64 s[10:11], |v46|, s60
	s_nop 1
	v_cndmask_b32_e64 v46, v46, v48, s[10:11]
	v_cndmask_b32_e32 v48, 0, v153, vcc
	v_sub_f32_e32 v46, v46, v48
	v_mul_f32_e32 v48, 0xbfb8aa3b, v51
	v_exp_f32_e32 v48, v48
	v_add_f32_e32 v46, v43, v46
	v_add_f32_e32 v48, 1.0, v48
	v_rcp_f32_e32 v59, v48
	s_nop 0
	v_fma_f32 v48, v10, v59, v57
	v_cmp_gt_f32_e32 vcc, s29, v48
	s_nop 1
	v_cndmask_b32_e64 v50, 0, 32, vcc
	v_ldexp_f32 v48, v48, v50
	v_log_f32_e32 v48, v48
	s_nop 0
	v_mul_f32_e32 v50, 0x3f317217, v48
	v_fma_f32 v50, v48, s69, -v50
	v_fmac_f32_e32 v50, 0x3377d1cf, v48
	v_fmac_f32_e32 v50, 0x3f317217, v48
	v_cmp_lt_f32_e64 s[10:11], |v48|, s60
	s_nop 1
	v_cndmask_b32_e64 v48, v48, v50, s[10:11]
	v_cndmask_b32_e32 v50, 0, v153, vcc
	v_sub_f32_e32 v48, v48, v50
	v_mul_f32_e32 v50, 0xbfb8aa3b, v53
	v_exp_f32_e32 v50, v50
	v_add_f32_e32 v48, v46, v48
	v_add_f32_e32 v50, 1.0, v50
	v_rcp_f32_e32 v60, v50
	s_nop 0
	v_fma_f32 v50, v10, v60, v57
	v_cmp_gt_f32_e32 vcc, s29, v50
	s_nop 1
	v_cndmask_b32_e64 v51, 0, 32, vcc
	v_ldexp_f32 v50, v50, v51
	v_log_f32_e32 v50, v50
	s_nop 0
	v_mul_f32_e32 v51, 0x3f317217, v50
	v_fma_f32 v51, v50, s69, -v51
	v_fmac_f32_e32 v51, 0x3377d1cf, v50
	v_fmac_f32_e32 v51, 0x3f317217, v50
	v_cmp_lt_f32_e64 s[10:11], |v50|, s60
	s_nop 1
	v_cndmask_b32_e64 v50, v50, v51, s[10:11]
	v_cndmask_b32_e32 v51, 0, v153, vcc
	v_sub_f32_e32 v50, v50, v51
	v_mul_f32_e32 v51, 0xbfb8aa3b, v54
	v_exp_f32_e32 v51, v51
	v_add_f32_e32 v50, v48, v50
	v_add_f32_e32 v51, 1.0, v51
	v_rcp_f32_e32 v61, v51
	s_nop 0
	v_fma_f32 v51, v10, v61, v57
	v_cmp_gt_f32_e32 vcc, s29, v51
	s_nop 1
	v_cndmask_b32_e64 v53, 0, 32, vcc
	v_ldexp_f32 v51, v51, v53
	v_log_f32_e32 v51, v51
	s_nop 0
	v_mul_f32_e32 v53, 0x3f317217, v51
	v_fma_f32 v53, v51, s69, -v53
	v_fmac_f32_e32 v53, 0x3377d1cf, v51
	v_fmac_f32_e32 v53, 0x3f317217, v51
	v_cmp_lt_f32_e64 s[10:11], |v51|, s60
	s_nop 1
	v_cndmask_b32_e64 v51, v51, v53, s[10:11]
	v_cndmask_b32_e32 v53, 0, v153, vcc
	v_sub_f32_e32 v51, v51, v53
	v_mul_f32_e32 v53, 0xbfb8aa3b, v62
	v_exp_f32_e32 v53, v53
	v_add_f32_e32 v51, v50, v51
	v_add_f32_e32 v53, 1.0, v53
	v_rcp_f32_e32 v62, v53
	s_nop 0
	v_fma_f32 v53, v10, v62, v57
	v_cmp_gt_f32_e32 vcc, s29, v53
	s_nop 1
	v_cndmask_b32_e64 v54, 0, 32, vcc
	v_ldexp_f32 v53, v53, v54
	v_log_f32_e32 v53, v53
	s_nop 0
	v_mul_f32_e32 v54, 0x3f317217, v53
	v_fma_f32 v54, v53, s69, -v54
	v_fmac_f32_e32 v54, 0x3377d1cf, v53
	v_fmac_f32_e32 v54, 0x3f317217, v53
	v_cmp_lt_f32_e64 s[10:11], |v53|, s60
	s_nop 1
	v_cndmask_b32_e64 v53, v53, v54, s[10:11]
	v_cndmask_b32_e32 v54, 0, v153, vcc
	v_sub_f32_e32 v53, v53, v54
	s_waitcnt vmcnt(0)
	v_mul_f32_e32 v54, 0xbfb8aa3b, v63
	v_exp_f32_e32 v54, v54
	v_add_f32_e32 v53, v51, v53
	v_add_f32_e32 v54, 1.0, v54
	v_rcp_f32_e32 v63, v54
	s_nop 0
	v_fma_f32 v54, v10, v63, v57
	v_cmp_gt_f32_e32 vcc, s29, v54
	v_fmac_f32_e32 v57, v10, v64
	s_nop 0
	v_cndmask_b32_e64 v65, 0, 32, vcc
	v_ldexp_f32 v54, v54, v65
	v_log_f32_e32 v54, v54
	s_nop 0
	v_mul_f32_e32 v65, 0x3f317217, v54
	v_fma_f32 v65, v54, s69, -v65
	v_fmac_f32_e32 v65, 0x3377d1cf, v54
	v_fmac_f32_e32 v65, 0x3f317217, v54
	v_cmp_lt_f32_e64 s[10:11], |v54|, s60
	s_nop 1
	v_cndmask_b32_e64 v54, v54, v65, s[10:11]
	v_cndmask_b32_e32 v65, 0, v153, vcc
	v_cmp_gt_f32_e32 vcc, s29, v57
	v_sub_f32_e32 v54, v54, v65
	v_add_f32_e32 v54, v53, v54
	v_cndmask_b32_e64 v65, 0, 32, vcc
	v_ldexp_f32 v57, v57, v65
	v_log_f32_e32 v57, v57
	s_nop 0
	v_mul_f32_e32 v65, 0x3f317217, v57
	v_fma_f32 v65, v57, s69, -v65
	v_fmac_f32_e32 v65, 0x3377d1cf, v57
	v_fmac_f32_e32 v65, 0x3f317217, v57
	v_cmp_lt_f32_e64 s[10:11], |v57|, s60
	s_nop 1
	v_cndmask_b32_e64 v57, v57, v65, s[10:11]
	v_cndmask_b32_e32 v65, 0, v153, vcc
	v_sub_f32_e32 v57, v57, v65
	v_add_f32_e32 v57, v54, v57
	ds_write_b32 v11, v57 offset:36864
	v_cvt_pk_bf16_f32 v66, v24, v161
	v_cvt_pk_bf16_f32 v67, v162, v163
	v_cvt_pk_bf16_f32 v68, v164, v165
	v_cvt_pk_bf16_f32 v69, v166, v167
	ds_write_b128 v31, v[66:69] offset:18432
	v_cvt_pk_bf16_f32 v12, v168, v169
	v_cvt_pk_bf16_f32 v13, v170, v171
	v_cvt_pk_bf16_f32 v14, v172, v173
	v_cvt_pk_bf16_f32 v15, v174, v175
	ds_write_b128 v31, v[12:15] offset:18448
	s_waitcnt lgkmcnt(0)
	s_barrier
	ds_read2st64_b32 v[12:13], v5 offset0:144 offset1:146
	ds_read2st64_b32 v[14:15], v5 offset0:148 offset1:150
	v_mov_b32_e32 v16, 0
	s_and_saveexec_b64 s[10:11], s[8:9]
	s_cbranch_execz .LBB0_1025
	v_cmp_lt_i32_e32 vcc, 1, v1
	s_mov_b64 s[20:21], 0
	s_and_saveexec_b64 s[22:23], vcc
	s_xor_b64 s[22:23], exec, s[22:23]
	s_cbranch_execnz .LBB0_1027
	s_andn2_saveexec_b64 s[22:23], s[22:23]
	s_cbranch_execnz .LBB0_1030
